# v25 (P5 x loads default) + x rows touched by idle waves during the P4->P5 grid barrier (on-die prefetch of the residual)
# baseline (speedup 1.0000x reference)
; __device__ __forceinline__ void xcd_barrier(const XcdBarrier& b) {
;     asm volatile("s_waitcnt vmcnt(0)" ::: "memory");
;     __syncthreads();
;     if (threadIdx.x == 0) {
;         unsigned* bar = b.bar;
;         __builtin_amdgcn_s_waitcnt(0);
;         unsigned nloc = b.st[0], nx = b.st[1];
;         if (nloc == 0u) { xcd_barrier_complete(bar, b.x, nloc, nx); b.st[0] = nloc; b.st[1] = nx; }
.LBB0_701:
	v_readlane_b32 s0, v238, 0
	v_readlane_b32 s1, v238, 1
	s_cmp_gt_i32 s1, 5
	s_cselect_b64 s[4:5], -1, 0
	s_and_b64 s[0:1], s[6:7], s[4:5]
	s_andn2_b64 vcc, exec, s[0:1]
	s_cbranch_vccnz .LBB0_757
	s_waitcnt vmcnt(0)
	s_waitcnt vmcnt(0)
	s_barrier
	s_cmp_eq_u32 s96, 0
	s_cbranch_scc1 .Lxpf_skip_s4
	s_cmpk_gt_u32 s2, 0xff
	s_cbranch_scc1 .Lxpf_skip_s4
	v_readlane_b32 s0, v238, 4
	v_readlane_b32 s1, v238, 5
	v_subrev_u32_e32 v2, 64, v0
	v_lshlrev_b32_e32 v2, 7, v2
	s_lshl_b32 s3, s2, 18
	s_add_u32 s0, s0, s3
	s_addc_u32 s1, s1, 0
	global_load_dword v239, v2, s[0:1]
	v_add_u32_e32 v2, 0xe000, v2
	global_load_dword v239, v2, s[0:1]
	v_add_u32_e32 v2, 0xe000, v2
	global_load_dword v239, v2, s[0:1]
	v_add_u32_e32 v2, 0xe000, v2
	global_load_dword v239, v2, s[0:1]
	s_cmp_gt_u32 s96, 4
	s_cbranch_scc1 .Lxpf_skip_s4
	v_add_u32_e32 v2, 0xe000, v2
	global_load_dword v239, v2, s[0:1]
.Lxpf_skip_s4:
	s_and_saveexec_b64 s[6:7], s[92:93]
	s_cbranch_execz .LBB0_756
	s_add_i32 s0, 0, 0x24220
	v_mov_b32_e32 v2, s0
	s_waitcnt vmcnt(0) expcnt(0) lgkmcnt(0)
	ds_read_b32 v4, v2
	s_add_i32 s0, 0, 0x24224
	v_mov_b32_e32 v2, s0
	ds_read_b32 v2, v2
	s_waitcnt lgkmcnt(1)
	v_cmp_ne_u32_e32 vcc, 0, v4
	s_cbranch_vccnz .LBB0_718
	v_readlane_b32 s0, v238, 2
	v_readlane_b32 s1, v238, 3
	s_load_dwordx2 s[12:13], s[0:1], 0x4
	s_add_u32 s0, s50, 0x4200
	s_addc_u32 s1, s51, 0
	s_add_u32 s10, s50, 0x4400
	s_addc_u32 s11, s51, 0
	s_waitcnt lgkmcnt(0)
	s_mul_i32 s3, s12, s52
	s_add_u32 s12, s50, 0x4500
	s_mul_i32 s3, s3, s13
	s_addc_u32 s13, s51, 0
	s_add_u32 s14, s50, 0x4600
	s_addc_u32 s15, s51, 0
	s_add_u32 s16, s50, 0x4700
	s_addc_u32 s17, s51, 0
	s_add_u32 s18, s50, 0x4800
	s_addc_u32 s19, s51, 0
	s_add_u32 s20, s50, 0x4900
	s_addc_u32 s21, s51, 0
	s_add_u32 s22, s50, 0x4a00
	s_addc_u32 s23, s51, 0
	s_add_u32 s24, s50, 0x4b00
	s_addc_u32 s25, s51, 0
	s_add_u32 s26, s50, 0x4c00
	s_addc_u32 s27, s51, 0
	s_add_u32 s28, s50, 0x4d00
	s_addc_u32 s29, s51, 0
	s_add_u32 s30, s50, 0x4e00
	s_addc_u32 s31, s51, 0
	s_add_u32 s34, s50, 0x4f00
	s_addc_u32 s35, s51, 0
	s_add_u32 s36, s50, 0x5000
	s_addc_u32 s37, s51, 0
	s_add_u32 s38, s50, 0x5100
	s_addc_u32 s39, s51, 0
	s_add_u32 s40, s50, 0x5200
	s_addc_u32 s41, s51, 0
	s_add_u32 s42, s50, 0x5300
	s_addc_u32 s43, s51, 0
	s_mov_b32 s33, 1
	v_mov_b32_e32 v18, 0
	s_branch .LBB0_706

; __global__ void __launch_bounds__(NWAVES * 64, 2) mk_fwd(Args args) {
	.amdhsa_kernel _Z6mk_fwd4Args
		.amdhsa_group_segment_fixed_size 0
		.amdhsa_private_segment_fixed_size 0
		.amdhsa_kernarg_size 472
		.amdhsa_user_sgpr_count 2
		.amdhsa_user_sgpr_dispatch_ptr 0
		.amdhsa_user_sgpr_queue_ptr 0
		.amdhsa_user_sgpr_kernarg_segment_ptr 1
		.amdhsa_user_sgpr_dispatch_id 0
		.amdhsa_user_sgpr_kernarg_preload_length 0
		.amdhsa_user_sgpr_kernarg_preload_offset 0
		.amdhsa_user_sgpr_private_segment_size 0
		.amdhsa_uses_dynamic_stack 0
		.amdhsa_enable_private_segment 0
		.amdhsa_system_sgpr_workgroup_id_x 1
		.amdhsa_system_sgpr_workgroup_id_y 0
		.amdhsa_system_sgpr_workgroup_id_z 0
		.amdhsa_system_sgpr_workgroup_info 0
		.amdhsa_system_vgpr_workitem_id 0
		.amdhsa_next_free_vgpr 240
		.amdhsa_next_free_sgpr 98
		.amdhsa_accum_offset 240
		.amdhsa_reserve_vcc 1
		.amdhsa_float_round_mode_32 0
		.amdhsa_float_round_mode_16_64 0
		.amdhsa_float_denorm_mode_32 3
		.amdhsa_float_denorm_mode_16_64 3
		.amdhsa_dx10_clamp 1
		.amdhsa_ieee_mode 1
		.amdhsa_fp16_overflow 0
		.amdhsa_tg_split 0
		.amdhsa_exception_fp_ieee_invalid_op 0
		.amdhsa_exception_fp_denorm_src 0
		.amdhsa_exception_fp_ieee_div_zero 0
		.amdhsa_exception_fp_ieee_overflow 0
		.amdhsa_exception_fp_ieee_underflow 0
		.amdhsa_exception_fp_ieee_inexact 0
		.amdhsa_exception_int_div_zero 0
	.end_amdhsa_kernel

; __global__ void __launch_bounds__(NWAVES * 64, 2) mk_fwd(Args args) {
amdhsa.kernels:
  - .agpr_count:     0
    .args:
      - .offset:         0
        .size:           216
        .value_kind:     by_value
      - .offset:         216
        .size:           4
        .value_kind:     hidden_block_count_x
      - .offset:         220
        .size:           4
        .value_kind:     hidden_block_count_y
      - .offset:         224
        .size:           4
        .value_kind:     hidden_block_count_z
      - .offset:         228
        .size:           2
        .value_kind:     hidden_group_size_x
      - .offset:         230
        .size:           2
        .value_kind:     hidden_group_size_y
      - .offset:         232
        .size:           2
        .value_kind:     hidden_group_size_z
      - .offset:         234
        .size:           2
        .value_kind:     hidden_remainder_x
      - .offset:         236
        .size:           2
        .value_kind:     hidden_remainder_y
      - .offset:         238
        .size:           2
        .value_kind:     hidden_remainder_z
      - .offset:         256
        .size:           8
        .value_kind:     hidden_global_offset_x
      - .offset:         264
        .size:           8
        .value_kind:     hidden_global_offset_y
      - .offset:         272
        .size:           8
        .value_kind:     hidden_global_offset_z
      - .offset:         280
        .size:           2
        .value_kind:     hidden_grid_dims
      - .offset:         336
        .size:           4
        .value_kind:     hidden_dynamic_lds_size
    .group_segment_fixed_size: 0
    .kernarg_segment_align: 8
    .kernarg_segment_size: 472
    .language:       OpenCL C
    .language_version:
      - 2
      - 0
    .max_flat_workgroup_size: 512
    .name:           _Z6mk_fwd4Args
    .private_segment_fixed_size: 0
    .sgpr_count:     104
    .sgpr_spill_count: 71
    .symbol:         _Z6mk_fwd4Args.kd
    .uniform_work_group_size: 1
    .uses_dynamic_stack: false
    .vgpr_count:     240
    .vgpr_spill_count: 0
    .wavefront_size: 64
